# as v29 plus: per-unit kind->(list base, count) branch chain in the SwiGLU GEMM unit loop replaced by a 3-instruction select (only kinds 1 and 6 run there)
# baseline (speedup 1.0000x reference)
.LBB0_1047:
	v_bfe_u32 v150, v6, 4, 2
	s_add_u32 s98, s72, 0x4a00000
	v_and_b32_e32 v149, 15, v6
	v_lshlrev_b32_e32 v2, 4, v150
	v_lshlrev_b32_e32 v4, 2, v6
	s_addc_u32 s99, s73, 0
	s_lshl_b32 s61, s2, 6
	v_lshl_or_b32 v2, v149, 6, v2
	s_lshl_b32 s2, s2, 13
	v_and_b32_e32 v4, 32, v4
	s_waitcnt lgkmcnt(0)
	v_bitop3_b32 v5, v2, s2, v4 bitop3:0xde
	s_lshl_b32 s2, s6, 5
	s_and_b32 s44, s2, 0x60
	s_lshl_b32 s2, s44, 7
	v_bitop3_b32 v2, v2, s2, v4 bitop3:0xde
	s_add_u32 s2, s64, 0x80
	s_waitcnt vmcnt(2)
	s_barrier
	s_addc_u32 s3, s65, 0
	s_add_i32 m0, s69, 0x18000
	s_nop 0
	global_load_lds_dwordx4 v1, s[2:3]
	s_mov_b32 s57, 0
	s_add_i32 m0, s69, 0x1a000
	s_nop 0
	global_load_lds_dwordx4 v146, s[2:3]
	s_add_u32 s2, s62, 0x80
	s_addc_u32 s3, s63, 0
	s_add_i32 m0, s69, 0x8000
	s_nop 0
	global_load_lds_dwordx4 v147, s[2:3]
	v_add_u32_e32 v151, 0, v2
	s_add_i32 m0, s69, 0xa000
	s_nop 0
	global_load_lds_dwordx4 v148, s[2:3]
	s_add_u32 s2, s64, 0x40080
	s_addc_u32 s3, s65, 0
	s_add_i32 m0, s69, 0x1c000
	s_nop 0
	global_load_lds_dwordx4 v1, s[2:3]
	v_add_u32_e32 v152, 0, v5
	s_add_i32 m0, s69, 0x1e000
	s_nop 0
	global_load_lds_dwordx4 v146, s[2:3]
	s_cmpk_lt_u32 s14, 0x100
	s_cselect_b64 s[72:73], -1, 0
	s_and_b32 s2, s14, 0xffffff00
	s_add_i32 s55, s2, 0
	s_add_i32 s55, s55, 0x24400
	s_waitcnt vmcnt(6)
	s_cmp_eq_u32 s42, 6
	s_movk_i32 s2, 0xfe98
	s_cselect_b32 s43, s2, 0xfffffde8
	s_cmp_eq_u32 s42, 3
	s_cselect_b32 s14, 0x48, 32
	s_lshl_b32 s15, s42, 12
	s_mov_b32 s17, 0
	s_mov_b32 s45, s19
	s_mov_b32 s38, 0
	s_barrier
	s_branch .Lunit3

.Lunit3:
	s_cmp_eq_u32 s42, 6
	s_cselect_b32 s18, s43, 0
	s_movk_i32 s2, 0xb0
	s_branch .LBB0_1071
